# hand-off waits (B1->S5, KV->X): L2 invalidate dropped, the consumed buffers are first-touch in the phase so no stale lines can exist
# baseline (speedup 1.0000x reference)
; template <int N> DI void wait_vm() { asm volatile("s_waitcnt vmcnt(%0)" ::"n"(N) : "memory"); }
; DI void unit_S5(const Params& p, char* lds, int l, int b, int g) {
;     ...
;     wait_count(WS_PTR(unsigned, OFF_HL) + 128 + l * 16 + b, 16u);
; #pragma unroll
;     for (int i = 0; i < 8; ++i) {
;         const int P = (wid * 8 + i) * 64 + lane, S = P ^ ((P >> 4) & 15);
;         __builtin_amdgcn_global_load_lds((const unsigned*)(Xg + (size_t)S * 8), (unsigned*)(Xl + P * 16), 16, 0, 0);
;     }
;     wait_vm<0>();
;     __syncthreads();
.Lxs_s5_ok:
.LBB0_671:
	s_or_b64 exec, exec, s[6:7]
	s_lshl_b32 s1, s1, 16
	s_lshl_b32 s0, s0, 20
	v_lshlrev_b32_e32 v51, 9, v104
	v_bfe_u32 v57, v50, 4, 2
	s_or_b32 s1, s0, s1
	v_readlane_b32 s6, v243, 0
	v_or_b32_e32 v62, v51, v56
	s_add_u32 s6, s6, s1
	v_readlane_b32 s1, v243, 1
	v_bitop3_b32 v52, v51, v57, v56 bitop3:0x36
	v_lshl_add_u32 v63, v62, 4, s69
	s_addc_u32 s7, s1, 0
	v_ashrrev_i32_e32 v53, 31, v52
	v_readfirstlane_b32 s1, v63
	v_lshl_add_u64 v[52:53], v[52:53], 4, s[6:7]
	s_mov_b32 m0, s1
	v_or_b32_e32 v63, 64, v62
	s_barrier
	global_load_lds_dwordx4 v[52:53], off
	v_lshrrev_b32_e32 v52, 4, v63
	v_bitop3_b32 v52, v52, v63, 7 bitop3:0x6c
	v_lshl_add_u32 v63, v63, 4, s69
	v_ashrrev_i32_e32 v53, 31, v52
	v_readfirstlane_b32 s1, v63
	v_lshl_add_u64 v[52:53], v[52:53], 4, s[6:7]
	s_mov_b32 m0, s1
	v_or_b32_e32 v63, 0x80, v62
	global_load_lds_dwordx4 v[52:53], off
	v_lshrrev_b32_e32 v52, 4, v63
	v_bitop3_b32 v52, v52, v63, 11 bitop3:0x6c
	v_lshl_add_u32 v63, v63, 4, s69
	v_ashrrev_i32_e32 v53, 31, v52
	v_readfirstlane_b32 s1, v63
	v_lshl_add_u64 v[52:53], v[52:53], 4, s[6:7]
	s_mov_b32 m0, s1
	v_or_b32_e32 v63, 0xc0, v62
	global_load_lds_dwordx4 v[52:53], off
	v_lshrrev_b32_e32 v52, 4, v63
	v_bitop3_b32 v52, v52, v63, 15 bitop3:0x6c
	v_lshl_add_u32 v63, v63, 4, s69
	v_ashrrev_i32_e32 v53, 31, v52
	v_readfirstlane_b32 s1, v63
	v_lshl_add_u64 v[52:53], v[52:53], 4, s[6:7]
	s_mov_b32 m0, s1
	v_or_b32_e32 v63, 0x100, v62
	s_movk_i32 s1, 0x100
	global_load_lds_dwordx4 v[52:53], off
	v_bitop3_b32 v52, v62, v57, s1 bitop3:0x36
	v_lshl_add_u32 v63, v63, 4, s69
	v_ashrrev_i32_e32 v53, 31, v52
	v_readfirstlane_b32 s1, v63
	v_lshl_add_u64 v[52:53], v[52:53], 4, s[6:7]
	s_mov_b32 m0, s1
	v_or_b32_e32 v63, 0x140, v62
	global_load_lds_dwordx4 v[52:53], off
	v_lshrrev_b32_e32 v52, 4, v63
	v_bitop3_b32 v52, v52, v63, 7 bitop3:0x6c
	v_lshl_add_u32 v63, v63, 4, s69
	v_ashrrev_i32_e32 v53, 31, v52
	v_readfirstlane_b32 s1, v63
	v_lshl_add_u64 v[52:53], v[52:53], 4, s[6:7]
	s_mov_b32 m0, s1
	v_or_b32_e32 v63, 0x180, v62
	global_load_lds_dwordx4 v[52:53], off
	v_lshrrev_b32_e32 v52, 4, v63
	v_bitop3_b32 v52, v52, v63, 11 bitop3:0x6c
	v_lshl_add_u32 v63, v63, 4, s69
	v_ashrrev_i32_e32 v53, 31, v52
	v_readfirstlane_b32 s1, v63
	v_lshl_add_u64 v[52:53], v[52:53], 4, s[6:7]
	s_mov_b32 m0, s1
	v_or_b32_e32 v62, 0x1c0, v62
	global_load_lds_dwordx4 v[52:53], off
	v_lshrrev_b32_e32 v52, 4, v62
	v_bitop3_b32 v52, v52, v62, 15 bitop3:0x6c
	v_lshl_add_u32 v62, v62, 4, s69
	v_ashrrev_i32_e32 v53, 31, v52
	v_readfirstlane_b32 s1, v62
	v_lshl_add_u64 v[52:53], v[52:53], 4, s[6:7]
	s_mov_b32 m0, s1
	v_and_b32_e32 v50, 0xffffffc0, v50
	global_load_lds_dwordx4 v[52:53], off
	s_waitcnt vmcnt(0)
	v_add_u32_e32 v50, 0, v50
	v_lshlrev_b32_e32 v52, 2, v54
	v_mul_u32_u24_e32 v53, 0x840, v57
	s_waitcnt lgkmcnt(0)
	v_add3_u32 v121, v50, v52, v53
	v_lshl_or_b32 v100, v54, 4, v57
	s_mov_b32 s1, 0
	v_mov_b32_e32 v50, v121
	s_waitcnt vmcnt(0) lgkmcnt(0)
	s_barrier

; DI void unit_X(const Params& p, char* lds, int l, int chunk) {
;     ...
;     if (l == 0) wait_count(WS_PTR(unsigned, OFF_HL) + 64 + l * 16 + b, 8u); else __syncthreads();
.Lxs_x_ok:
	s_waitcnt lgkmcnt(0)
.LBB0_822:
	s_or_b64 exec, exec, s[6:7]
	s_waitcnt lgkmcnt(0)
	s_barrier
